# conv walker set-up: the three halo-row loads issued together; scan: uniform tile-skip masks negated on the scalar unit
# baseline (speedup 1.0000x reference)
; #define LAS __attribute__((address_space(3)))
; __device__ __forceinline__ unsigned pk2(float lo, float hi) { unsigned r; asm volatile("v_cvt_pk_bf16_f32 %0, %1, %2" : "=v"(r) : "v"(lo), "v"(hi)); return r; }
; template <bool DRY>
; __device__ __forceinline__ void ssd_chunk(SsdRegs& R, f32x4 (&st)[2], LAS unsigned char* L, bf16_t* BIG, const float* DT, float* SSQY, const SsdItem& I, int c, int tid, int lane, int wave, int li, int pi, int c16, int q4) {
;     ...
;     {
;         const int l = 16 * li + c16; const float acs_l = *(const LAS float*)(SCW + l * 4);
; #pragma unroll
;         for (int t = 0; t < 2; ++t) {
;             const int si = 2 * pi + t;
;             u32x2 w; w.x = 0u; w.y = 0u;
;             if (si <= li) {
;                 f32x4 d = (f32x4){0.f, 0.f, 0.f, 0.f};
; #pragma unroll
;                 for (int kk = 0; kk < 4; ++kk) d = __builtin_amdgcn_mfma_f32_16x16x32_bf16(SSD_FRAG(BS, PC, 16 * si, kk), cfr[kk], d, 0, 0, 0);
;                 float gv[4];
;                 const f32x4 acs_s = *(const LAS f32x4*)(SCW + (16 * si + 4 * q4) * 4), dt_s = *(const LAS f32x4*)(SCW + 256 + (16 * si + 4 * q4) * 4);
; #pragma unroll
;                 for (int e = 0; e < 4; ++e) gv[e] = d[e] * __expf(acs_l - acs_s[e]) * dt_s[e];
;                 if (si == li) {
; #pragma unroll
;                     for (int e = 0; e < 4; ++e) gv[e] = (4 * q4 + e <= c16) ? gv[e] : 0.f;
;                 }
;                 w.x = pk2(gv[0], gv[1]); w.y = pk2(gv[2], gv[3]);
;             }
;             *(LAS u32x2*)(L + GG + l * PT + (16 * si + 4 * q4) * 2) = w;
;         }
.LBB0_727:
	ds_read_b128 v[70:73], v131
	ds_read_b128 v[66:69], v131 offset:64
	ds_read_b128 v[62:65], v131 offset:128
	ds_read_b128 v[58:61], v131 offset:192
	ds_read_b32 v76, v132
	v_mov_b32_e32 v106, 0
	s_not_b64 s[22:23], s[88:89]
	s_andn2_b64 vcc, exec, s[88:89]
	v_mov_b32_e32 v107, v106
	s_cbranch_vccnz .LBB0_729
	ds_read_b128 v[144:147], v133 offset:17408
	ds_read_b128 v[148:151], v133 offset:17472
	ds_read_b128 v[176:179], v133 offset:17536
	ds_read_b128 v[180:183], v133 offset:17600
	ds_read_b128 v[184:187], v134
	ds_read_b128 v[152:155], v134 offset:256
	s_waitcnt lgkmcnt(5)
	v_mfma_f32_16x16x32_bf16 v[144:147], v[144:147], v[70:73], 0
	s_waitcnt lgkmcnt(4)
	v_mfma_f32_16x16x32_bf16 v[144:147], v[148:151], v[66:69], v[144:147]
	s_waitcnt lgkmcnt(3)
	v_mfma_f32_16x16x32_bf16 v[144:147], v[176:179], v[62:65], v[144:147]
	s_waitcnt lgkmcnt(2)
	v_mfma_f32_16x16x32_bf16 v[144:147], v[180:183], v[58:61], v[144:147]
	s_waitcnt lgkmcnt(1)
	v_sub_f32_e32 v106, v76, v184
	v_sub_f32_e32 v107, v76, v185
	v_exp_f32_e32 v106, v106
	v_exp_f32_e32 v107, v107
	v_sub_f32_e32 v143, v76, v186
	v_pk_mul_f32 v[106:107], v[144:145], v[106:107]
	v_exp_f32_e32 v144, v143
	v_sub_f32_e32 v143, v76, v187
	v_exp_f32_e32 v145, v143
	s_waitcnt lgkmcnt(0)
	v_pk_mul_f32 v[106:107], v[152:153], v[106:107]
	v_pk_mul_f32 v[144:145], v[146:147], v[144:145]
	s_nop 0
	v_pk_mul_f32 v[144:145], v[154:155], v[144:145]
	v_cndmask_b32_e64 v143, v106, 0, s[6:7]
	v_cndmask_b32_e64 v146, 0, v107, s[8:9]
	v_cndmask_b32_e64 v147, v144, 0, s[10:11]
	v_cndmask_b32_e64 v148, v145, 0, s[12:13]
	v_cndmask_b32_e64 v106, v106, v143, s[4:5]
	v_cndmask_b32_e64 v107, v107, v146, s[4:5]
	v_cndmask_b32_e64 v144, v144, v147, s[4:5]
	v_cndmask_b32_e64 v145, v145, v148, s[4:5]
	v_cvt_pk_bf16_f32 v106, v106, v107
	v_cvt_pk_bf16_f32 v107, v144, v145
.LBB0_729:
	v_add_u32_e32 v144, s68, v113
	ds_write_b64 v144, v[106:107]
	s_not_b64 s[24:25], s[84:85]
	s_andn2_b64 vcc, exec, s[84:85]
	s_mov_b64 s[0:1], -1
	s_cbranch_vccnz .LBB0_731
	s_mov_b64 s[0:1], 0

; __device__ __forceinline__ void phase_ssd_conv_dt(const Args& a, int j) {
;     ...
;     bf16_t* BIG = (bf16_t*)(a.ws + WS_BIG); const bf16_t* HALO = (const bf16_t*)(a.ws + WS_HALO);
;     const float* cw = a.in[6] + (size_t)j * 4 * 4096; const float* cb = a.in[7] + (size_t)j * 4096;
;     const int cg8 = gw & 7, bs = gw >> 3, c0 = cg8 * 512 + lane * 8;
;     float wt[4][8], bb[8];
; #pragma unroll
;     for (int h = 0; h < 2; ++h) {
; #pragma unroll
;         for (int k = 0; k < 4; ++k) { const f32x4 t = *(const f32x4*)(cw + k * 4096 + c0 + 4 * h);
; #pragma unroll
;             for (int e = 0; e < 4; ++e) wt[k][4 * h + e] = t[e]; }
;         const f32x4 t = *(const f32x4*)(cb + c0 + 4 * h);
; #pragma unroll
;         for (int e = 0; e < 4; ++e) bb[4 * h + e] = t[e];
;     }
;     float h0[8], h1[8], h2[8];
;     if ((bs & 63) == 0) {
; #pragma unroll
;         for (int e = 0; e < 8; ++e) { h0[e] = 0.f; h1[e] = 0.f; h2[e] = 0.f; }
;     } else {
;         const bf16_t* hp = HALO + (size_t)(bs - 1) * 3 * 4096 + c0;
;         unpack8(*(const uint4*)hp, h0); unpack8(*(const uint4*)(hp + 4096), h1); unpack8(*(const uint4*)(hp + 8192), h2);
;     }
.LBB0_794:
	s_and_b64 vcc, exec, s[6:7]
	s_cbranch_vccz .LBB0_821
	v_and_b32_e32 v100, 63, v1
	v_ashrrev_i32_e32 v5, 6, v1
	s_waitcnt vmcnt(0) lgkmcnt(0)
	v_lshlrev_b32_e32 v2, 9, v5
	s_waitcnt lgkmcnt(0)
	v_lshlrev_b32_e32 v4, 3, v100
	s_movk_i32 s2, 0xe00
	v_and_or_b32 v4, v2, s2, v4
	v_lshlrev_b32_e32 v2, 2, v4
	v_lshl_add_u64 v[10:11], s[4:5], 0, v[2:3]
	v_add_co_u32_e32 v14, vcc, 0x4000, v10
	s_mov_b64 s[2:3], 0x4000
	s_nop 0
	v_addc_co_u32_e32 v15, vcc, 0, v11, vcc
	global_load_dwordx4 v[18:21], v2, s[4:5] offset:16
	global_load_dwordx4 v[22:25], v2, s[4:5]
	v_lshl_add_u64 v[12:13], v[10:11], 0, s[2:3]
	global_load_dwordx4 v[26:29], v[14:15], off
	global_load_dwordx4 v[30:33], v[12:13], off offset:16
	s_mov_b64 s[2:3], 0x8000
	v_add_co_u32_e32 v14, vcc, 0x8000, v10
	v_lshl_add_u64 v[12:13], v[10:11], 0, s[2:3]
	s_nop 0
	v_addc_co_u32_e32 v15, vcc, 0, v11, vcc
	s_mov_b64 s[10:11], 0xc000
	global_load_dwordx4 v[34:37], v[14:15], off
	global_load_dwordx4 v[38:41], v[12:13], off offset:16
	v_lshl_add_u64 v[12:13], v[10:11], 0, s[10:11]
	v_add_co_u32_e32 v10, vcc, 0xc000, v10
	s_nop 1
	v_addc_co_u32_e32 v11, vcc, 0, v11, vcc
	global_load_dwordx4 v[42:45], v[10:11], off
	global_load_dwordx4 v[46:49], v[12:13], off offset:16
	global_load_dwordx4 v[50:53], v2, s[0:1] offset:16
	global_load_dwordx4 v[54:57], v2, s[0:1]
	v_readlane_b32 s0, v253, 58
	s_nop 1
	v_add_u32_e32 v5, s0, v5
	v_and_b32_e32 v2, 0x1f8, v5
	v_cmp_ne_u32_e32 vcc, 0, v2
	v_mov_b32_e32 v2, v3
	v_ashrrev_i32_e32 v10, 3, v5
	v_mov_b64_e32 v[78:79], v[2:3]
	v_mov_b64_e32 v[80:81], v[2:3]
	v_mov_b64_e32 v[82:83], v[2:3]
	v_mov_b64_e32 v[88:89], v[2:3]
	v_mov_b64_e32 v[68:69], v[2:3]
	v_mov_b64_e32 v[72:73], v[2:3]
	v_mov_b64_e32 v[76:77], v[2:3]
	v_mov_b64_e32 v[84:85], v[2:3]
	v_mov_b64_e32 v[64:65], v[2:3]
	v_mov_b64_e32 v[66:67], v[2:3]
	v_mov_b64_e32 v[70:71], v[2:3]
	v_mov_b64_e32 v[74:75], v[2:3]
	s_and_saveexec_b64 s[0:1], vcc
	s_cbranch_execz .LBB0_797
	v_lshl_add_u32 v12, v10, 1, v10
	v_ashrrev_i32_e32 v13, 31, v12
	v_readlane_b32 s2, v254, 1
	v_lshlrev_b64 v[12:13], 13, v[12:13]
	v_readlane_b32 s3, v254, 2
	v_lshlrev_b32_e32 v2, 1, v4
	s_nop 0
	v_lshl_add_u64 v[12:13], s[2:3], 0, v[12:13]
	v_lshl_add_u64 v[16:17], v[12:13], 0, v[2:3]
	v_add_co_u32_e32 v12, vcc, 0xffffa000, v16
	s_movk_i32 s2, 0xc000
	s_nop 0
	v_addc_co_u32_e32 v13, vcc, -1, v17, vcc
	global_load_dwordx4 v[112:115], v[12:13], off
	v_add_co_u32_e32 v12, vcc, s2, v16
	s_nop 1
	v_addc_co_u32_e32 v13, vcc, -1, v17, vcc
	global_load_dwordx4 v[116:119], v[12:13], off
	s_movk_i32 s2, 0xe000
	v_add_co_u32_e32 v12, vcc, s2, v16
	s_nop 1
	v_addc_co_u32_e32 v13, vcc, -1, v17, vcc
	global_load_dwordx4 v[12:15], v[12:13], off
	s_waitcnt vmcnt(0)
	v_lshlrev_b32_e32 v75, 16, v112
	v_and_b32_e32 v74, 0xffff0000, v112
	v_lshlrev_b32_e32 v71, 16, v113
	v_and_b32_e32 v70, 0xffff0000, v113
	v_lshlrev_b32_e32 v67, 16, v114
	v_and_b32_e32 v66, 0xffff0000, v114
	v_lshlrev_b32_e32 v65, 16, v115
	v_and_b32_e32 v64, 0xffff0000, v115
	v_lshlrev_b32_e32 v85, 16, v116
	v_and_b32_e32 v84, 0xffff0000, v116
	v_lshlrev_b32_e32 v77, 16, v117
	v_and_b32_e32 v76, 0xffff0000, v117
	v_lshlrev_b32_e32 v73, 16, v118
	v_and_b32_e32 v72, 0xffff0000, v118
	v_lshlrev_b32_e32 v69, 16, v119
	v_and_b32_e32 v68, 0xffff0000, v119
	v_lshlrev_b32_e32 v89, 16, v12
	v_and_b32_e32 v88, 0xffff0000, v12
	v_lshlrev_b32_e32 v83, 16, v13
	v_and_b32_e32 v82, 0xffff0000, v13
	v_lshlrev_b32_e32 v81, 16, v14
	v_and_b32_e32 v80, 0xffff0000, v14
	v_lshlrev_b32_e32 v79, 16, v15
	v_and_b32_e32 v78, 0xffff0000, v15
